# INB now parks 7 stores per wave (rg4 second half via v188-191 constants), trickled from iteration 1
# baseline (speedup 1.0000x reference)
; #define PG8_STAGE(bufoff, gbase, voff) do { _Pragma("unroll") for (int _i = 0; _i < 2; ++_i) \
;         __builtin_amdgcn_global_load_lds((const unsigned*)((const char*)(gbase) + (voff)[_i]), (PG8_LAS unsigned*)(lds + (bufoff) + ldsw + _i * 8192), 16, 0, 0); } while (0)
; #define PG8_LDA(dst, b, h) do { _Pragma("unroll") for (int m = 0; m < 4; ++m) _Pragma("unroll") for (int k = 0; k < 2; ++k) dst[m][k] = *(const PG8_LAS bf16x8*)(lds + PG8_SA(b, h) + aoff + m * 2048 + k * 1024); } while (0)
; #define PG8_LDB(dst, b, h) do { _Pragma("unroll") for (int n = 0; n < 2; ++n) _Pragma("unroll") for (int k = 0; k < 2; ++k) dst[n][k] = *(const PG8_LAS bf16x8*)(lds + PG8_SB(b, h) + boff + n * 2048 + k * 1024); } while (0)
; #define PG8_SCHED __builtin_amdgcn_sched_barrier(0)
;     ...
;         const char* nA = has_next ? (const char*)g.A + (size_t)nxt.pm * tstep : cA; const char* nB = has_next ? (const char*)g.Bt + (size_t)nxt.pn * tstep : cB;
;         for (int t = 0; t < nt; t += 2) {
;             const bool last = (t == nt - 2);
;             const char* a1 = cA + (size_t)(t + 1) * kstep;
;             const char* a2 = last ? nA : cA + (size_t)(t + 2) * kstep; const char* b2 = last ? nB : cB + (size_t)(t + 2) * kstep;
;             const char* a3 = a2 + kstep; const char* b3 = b2 + kstep;
;             PG8_LDB(B0, 0, 0); PG8_LDB(B1, 0, 1); PG8_SCHED; PG8_LDA(At, 0, 0); PG8_STAGE(PG8_SA(1, 1), a1 + hstep, voffA);
.LBB0_531:
	s_ashr_i32 s7, s6, 31
	s_lshl_b64 s[18:19], s[6:7], 19
	s_add_u32 s18, s46, s18
	s_addc_u32 s19, s47, s19
	s_and_b64 s[20:21], s[36:37], exec
	s_cselect_b32 s2, s19, s25
	s_cselect_b32 s5, s18, s24
	s_ashr_i32 s17, s16, 31
	s_lshl_b64 s[20:21], s[16:17], 19
	v_readlane_b32 s26, v253, 14
	v_readlane_b32 s27, v253, 15
	s_add_u32 s20, s26, s20
	s_addc_u32 s21, s27, s21
	s_and_b64 s[26:27], s[36:37], exec
	s_cselect_b32 s7, s21, s23
	s_cselect_b32 s17, s20, s22
	s_add_u32 s24, s24, 0x40080
	s_addc_u32 s25, s25, 0
	s_add_u32 s39, s22, 0x100
	s_addc_u32 s55, s23, 0
	s_mov_b32 s56, -2
	s_cmp_eq_u32 s101, 7
	s_cbranch_scc0 .Lpkb_nomove
	v_mov_b32_e32 v188, v206
	v_mov_b32_e32 v189, v207
	v_mov_b32_e32 v190, v208
	v_mov_b32_e32 v191, v209
.Lpkb_nomove:
.LBB0_532:
	s_waitcnt lgkmcnt(0)
	v_add_u32_e32 v124, s51, v197
	s_waitcnt lgkmcnt(0)
	v_add_u32_e32 v156, s52, v197
	ds_read_b128 v[112:115], v124
	ds_read_b128 v[116:119], v124 offset:1024
	ds_read_b128 v[120:123], v124 offset:2048
	ds_read_b128 v[124:127], v124 offset:3072
	ds_read_b128 v[144:147], v156
	ds_read_b128 v[148:151], v156 offset:1024
	ds_read_b128 v[152:155], v156 offset:2048
	ds_read_b128 v[156:159], v156 offset:3072
	s_add_u32 s22, s24, 0xfffc0080
	s_addc_u32 s23, s25, -1
	s_cmp_eq_u32 s56, 12
	s_cselect_b32 s27, s2, s23
	s_cselect_b32 s26, s5, s22
	s_cselect_b32 s23, s7, s55
	s_cselect_b32 s22, s17, s39
	v_lshl_add_u64 v[218:219], s[24:25], 0, v[184:185]
	s_add_i32 m0, s29, 0xc000
	ds_read_b128 v[160:163], v200
	ds_read_b128 v[164:167], v200 offset:1024
	ds_read_b128 v[168:171], v200 offset:2048
	ds_read_b128 v[192:195], v200 offset:3072
	ds_read_b128 v[202:205], v200 offset:4096
	ds_read_b128 v[206:209], v200 offset:5120
	ds_read_b128 v[210:213], v200 offset:6144
	ds_read_b128 v[214:217], v200 offset:7168
	global_load_lds_dwordx4 v[218:219], off
	v_lshl_add_u64 v[218:219], s[24:25], 0, v[186:187]
	s_add_i32 m0, s29, 0xe000
	s_nop 0
	global_load_lds_dwordx4 v[218:219], off
	s_and_b32 s101, s101, 0xff
	s_cbranch_scc0 .Lpkb_w8a
	s_cmp_lt_i32 s56, 0
	s_cbranch_scc1 .Lpkb_w8a
	s_cmp_eq_u32 s101, 7
	s_cbranch_scc1 .Lpkb_s0
	s_cmp_eq_u32 s101, 6
	s_cbranch_scc1 .Lpkb_s1
	s_cmp_eq_u32 s101, 5
	s_cbranch_scc1 .Lpkb_s2
	s_cmp_eq_u32 s101, 4
	s_cbranch_scc1 .Lpkb_s3
	s_cmp_eq_u32 s101, 3
	s_cbranch_scc1 .Lpkb_s4
	s_cmp_eq_u32 s101, 2
	s_cbranch_scc1 .Lpkb_s5
	global_store_dwordx4 v[254:255], v[248:251], off offset:64
	s_branch .Lpkb_w9a
.Lpkb_s0:
	global_store_dwordx4 v[254:255], v[188:191], off offset:64
	v_add_co_u32_e32 v254, vcc, s100, v254
	s_nop 1
	v_addc_co_u32_e32 v255, vcc, 0, v255, vcc
	s_branch .Lpkb_w9a

; #define PG8_STAGE(bufoff, gbase, voff) do { _Pragma("unroll") for (int _i = 0; _i < 2; ++_i) \
;         __builtin_amdgcn_global_load_lds((const unsigned*)((const char*)(gbase) + (voff)[_i]), (PG8_LAS unsigned*)(lds + (bufoff) + ldsw + _i * 8192), 16, 0, 0); } while (0)
; #define PG8_LDA(dst, b, h) do { _Pragma("unroll") for (int m = 0; m < 4; ++m) _Pragma("unroll") for (int k = 0; k < 2; ++k) dst[m][k] = *(const PG8_LAS bf16x8*)(lds + PG8_SA(b, h) + aoff + m * 2048 + k * 1024); } while (0)
; #define PG8_LDB(dst, b, h) do { _Pragma("unroll") for (int n = 0; n < 2; ++n) _Pragma("unroll") for (int k = 0; k < 2; ++k) dst[n][k] = *(const PG8_LAS bf16x8*)(lds + PG8_SB(b, h) + boff + n * 2048 + k * 1024); } while (0)
; #define PG8_WAIT_V(n) asm volatile("s_waitcnt vmcnt(" #n ")" ::: "memory")
; #define PG8_WAIT_L(n) asm volatile("s_waitcnt lgkmcnt(" #n ")" ::: "memory")
; #define PG8_BAR __builtin_amdgcn_s_barrier()
;     ...
;         for (int t = 0; t < nt; t += 2) {
;             const bool last = (t == nt - 2);
;             const char* a1 = cA + (size_t)(t + 1) * kstep;
;             const char* a2 = last ? nA : cA + (size_t)(t + 2) * kstep; const char* b2 = last ? nB : cB + (size_t)(t + 2) * kstep;
;             const char* a3 = a2 + kstep; const char* b3 = b2 + kstep;
;             PG8_LDB(B0, 0, 0); PG8_LDB(B1, 0, 1); PG8_SCHED; PG8_LDA(At, 0, 0); PG8_STAGE(PG8_SA(1, 1), a1 + hstep, voffA);
;             PG8_WAIT_V(8); PG8_WAIT_L(0); PG8_BAR; PG8_MMA(0, 0, At, B0); PG8_MMA(0, 1, At, B1); PG8_BAR; PG8_SCHED;
;             PG8_LDA(At, 0, 1); PG8_STAGE(PG8_SB(0, 0), b2, voffB); PG8_STAGE(PG8_SB(0, 1), b2 + hstepB, voffB); PG8_STAGE(PG8_SA(0, 0), a2, voffA);
;             PG8_WAIT_V(8); PG8_WAIT_L(0); PG8_BAR; PG8_MMA(1, 0, At, B0); PG8_MMA(1, 1, At, B1); PG8_BAR; PG8_SCHED;
;             PG8_LDB(B0, 1, 0); PG8_LDB(B1, 1, 1); PG8_SCHED; PG8_LDA(At, 1, 0); PG8_STAGE(PG8_SA(0, 1), a2 + hstep, voffA);
;             PG8_WAIT_V(8); PG8_WAIT_L(0); PG8_BAR; PG8_MMA(0, 0, At, B0); PG8_MMA(0, 1, At, B1); PG8_BAR; PG8_SCHED;
;             PG8_LDA(At, 1, 1); PG8_STAGE(PG8_SB(1, 0), b3, voffB); PG8_STAGE(PG8_SB(1, 1), b3 + hstepB, voffB); PG8_STAGE(PG8_SA(1, 0), a3, voffA);
;             PG8_WAIT_V(8); PG8_WAIT_L(0); PG8_BAR; PG8_MMA(1, 0, At, B0); PG8_MMA(1, 1, At, B1); PG8_BAR; PG8_SCHED;
;         }
;         if constexpr (ALIGN_EPI) { if (wr == 0) PG8_BAR; }
.Lpkb_t:
	s_add_i32 s56, s56, 2
	s_add_u32 s24, s24, 0x100
	s_addc_u32 s25, s25, 0
	s_add_u32 s39, s39, 0x100
	s_addc_u32 s55, s55, 0
	s_cmp_gt_u32 s56, 13
	s_cbranch_scc0 .LBB0_532
	v_mov_b32_e32 v188, 0x800
	v_mov_b32_e32 v189, 0
	v_mov_b32_e32 v190, 0x7ff
	v_mov_b32_e32 v191, 0
	s_and_b64 vcc, exec, s[14:15]
	s_cbranch_vccz .LBB0_535
	s_barrier

; __device__ __forceinline__ float sum_x16(float v) { float a, b; swap16(v, a, b); return a + b; }
; __device__ __forceinline__ float sum_x32(float v) { float a, b; swap32(v, a, b); return a + b; }
; __device__ __forceinline__ void st16_wt(void* p, u32x4 v) { if (WT_STORES) asm volatile("global_store_dwordx4 %0, %1, off sc1\n\ts_nop 1" :: "v"(p), "v"(v) : "memory"); else *(u32x4*)p = v; }
; __device__ __forceinline__ unsigned cvt_pk_bf16(float lo, float hi) { unsigned r; asm volatile("v_cvt_pk_bf16_f32 %0, %1, %2" : "=v"(r) : "v"(lo), "v"(hi)); return r; }
;     __device__ __forceinline__ void operator()(const f32x4 (&acc)[2][2][4][2], const Unit& u, int wr, int wc, int fr, int fq, const bool reuse, PG8_LAS float* rscr, PG8_LAS const float* gains) const {
;     ...
; #pragma unroll
;         for (int ai = 0; ai < 2; ++ai)
; #pragma unroll
;             for (int m = 0; m < 4; ++m) {
;                 const int r = u.pm * BM + ai * HALF + wr * 64 + m * 16 + fr;
;                 const float rsv = (MODE == 0) ? 1.0f : rsvv[ai][m];
;                 f32x4 v[2][2];
; #pragma unroll
;                 for (int bj = 0; bj < 2; ++bj)
; #pragma unroll
;                     for (int n = 0; n < 2; ++n) v[bj][n] = acc[ai][bj][m][n] * rsv;
;                 if (type < 2) {
;                     float ss = 0.f;
; #pragma unroll
;                     for (int bj = 0; bj < 2; ++bj)
; #pragma unroll
;                         for (int n = 0; n < 2; ++n) { const f32x4 x = v[bj][n]; ss += (x[0] * x[0] + x[1] * x[1]) + (x[2] * x[2] + x[3] * x[3]); }
;                     ss = sum_x16(ss); ss = sum_x32(ss);
;                     const float inv = __builtin_amdgcn_rsqf(ss * (1.0f / 64.0f) + RMS_EPS);
; #pragma unroll
;                     for (int bj = 0; bj < 2; ++bj)
; #pragma unroll
;                         for (int n = 0; n < 2; ++n) v[bj][n] = v[bj][n] * gv[bj][n] * inv;
;                 }
;                 bf16_t* p = p0 + (size_t)(8 * ai + m) * step16;
; #pragma unroll
;                 for (int bj = 0; bj < 2; ++bj) { u32x4 w; w.x = cvt_pk_bf16(v[bj][0][0], v[bj][0][1]); w.y = cvt_pk_bf16(v[bj][0][2], v[bj][0][3]); w.z = cvt_pk_bf16(v[bj][1][0], v[bj][1][1]); w.w = cvt_pk_bf16(v[bj][1][2], v[bj][1][3]);
;                     st16_wt(p + 32 * bj, w); }
.LBB0_571:
	s_mul_i32 s22, s22, 10
	s_mov_b32 s23, s13
	v_lshl_add_u64 v[48:49], v[64:65], 0, s[22:23]
	v_mov_b32_e32 v254, v48
	v_mov_b32_e32 v255, v49
	s_mov_b32 s100, s12
	v_cvt_pk_bf16_f32 v62, v68, v69
	v_cvt_pk_bf16_f32 v63, v54, v55
	v_cvt_pk_bf16_f32 v64, v70, v71
	v_cvt_pk_bf16_f32 v65, v66, v67
	global_store_dwordx4 v[48:49], v[62:65], off
	v_cvt_pk_bf16_f32 v54, v60, v61
	v_cvt_pk_bf16_f32 v55, v50, v51
	v_cvt_pk_bf16_f32 v56, v56, v57
	v_cvt_pk_bf16_f32 v57, v52, v53
	v_mov_b32_e32 v206, v54
	v_mov_b32_e32 v207, v55
	v_mov_b32_e32 v208, v56
	v_mov_b32_e32 v209, v57
	v_pk_mul_f32 v[38:39], v[38:39], v[152:153] op_sel_hi:[1,0]
	v_pk_mul_f32 v[52:53], v[36:37], v[152:153] op_sel_hi:[1,0]
	v_pk_mul_f32 v[50:51], v[34:35], v[152:153] op_sel_hi:[1,0]
	v_pk_mul_f32 v[54:55], v[32:33], v[152:153] op_sel_hi:[1,0]
	v_pk_mul_f32 v[34:35], v[46:47], v[152:153] op_sel_hi:[1,0]
	v_pk_mul_f32 v[44:45], v[44:45], v[152:153] op_sel_hi:[1,0]
	v_pk_mul_f32 v[36:37], v[42:43], v[152:153] op_sel_hi:[1,0]
	s_and_b64 vcc, exec, s[38:39]
	v_pk_mul_f32 v[40:41], v[40:41], v[152:153] op_sel_hi:[1,0]
	s_cbranch_vccnz .LBB0_573
	v_mul_f32_e32 v32, v53, v53
	v_mul_f32_e32 v33, v39, v39
	v_fmac_f32_e32 v32, v52, v52
	v_fmac_f32_e32 v33, v38, v38
	v_add_f32_e32 v32, v32, v33
	v_mul_f32_e32 v33, v55, v55
	v_mul_f32_e32 v42, v51, v51
	v_fmac_f32_e32 v33, v54, v54
	v_fmac_f32_e32 v42, v50, v50
	v_add_f32_e32 v33, v33, v42
	v_add_f32_e32 v32, v32, v33
	v_mul_f32_e32 v33, v45, v45
	v_mul_f32_e32 v42, v35, v35
	v_fmac_f32_e32 v33, v44, v44
	v_fmac_f32_e32 v42, v34, v34
	v_add_f32_e32 v33, v33, v42
	v_add_f32_e32 v32, v33, v32
	v_mul_f32_e32 v33, v41, v41
	v_mul_f32_e32 v42, v37, v37
	v_fmac_f32_e32 v33, v40, v40
	v_fmac_f32_e32 v42, v36, v36
	v_add_f32_e32 v33, v33, v42
	v_add_f32_e32 v32, v33, v32
	v_mov_b32_e32 v33, v32
	s_nop 1
	v_permlane16_swap_b32_e32 v32, v33
	v_add_f32_e32 v32, v32, v33
	v_mov_b32_e32 v33, v32
	s_nop 1
	v_permlane32_swap_b32_e32 v32, v33
	v_add_f32_e32 v32, v32, v33
	v_fmamk_f32 v32, v32, 0x3c800000, v201
	v_rsq_f32_e32 v32, v32
	s_waitcnt lgkmcnt(0)
	v_pk_mul_f32 v[42:43], v[124:125], v[52:53]
	v_pk_mul_f32 v[38:39], v[126:127], v[38:39]
	v_pk_mul_f32 v[46:47], v[120:121], v[54:55]
	v_pk_mul_f32 v[52:53], v[42:43], v[32:33] op_sel_hi:[1,0]
	v_pk_mul_f32 v[42:43], v[122:123], v[50:51]
	v_pk_mul_f32 v[34:35], v[118:119], v[34:35]
	v_pk_mul_f32 v[50:51], v[42:43], v[32:33] op_sel_hi:[1,0]
	v_pk_mul_f32 v[42:43], v[116:117], v[44:45]
	v_pk_mul_f32 v[36:37], v[114:115], v[36:37]
	v_pk_mul_f32 v[40:41], v[112:113], v[40:41]
	v_pk_mul_f32 v[38:39], v[38:39], v[32:33] op_sel_hi:[1,0]
	v_pk_mul_f32 v[54:55], v[46:47], v[32:33] op_sel_hi:[1,0]
	v_pk_mul_f32 v[34:35], v[34:35], v[32:33] op_sel_hi:[1,0]
	v_pk_mul_f32 v[44:45], v[42:43], v[32:33] op_sel_hi:[1,0]
	v_pk_mul_f32 v[36:37], v[36:37], v[32:33] op_sel_hi:[1,0]
	v_pk_mul_f32 v[40:41], v[40:41], v[32:33] op_sel_hi:[1,0]
.LBB0_573:
	v_lshl_add_u64 v[32:33], v[48:49], 0, s[12:13]
	v_cvt_pk_bf16_f32 v46, v52, v53
	v_cvt_pk_bf16_f32 v47, v38, v39
	v_cvt_pk_bf16_f32 v48, v54, v55
	v_cvt_pk_bf16_f32 v49, v50, v51
	v_mov_b32_e32 v228, v46
	v_mov_b32_e32 v229, v47
	v_mov_b32_e32 v230, v48
	v_mov_b32_e32 v231, v49
	v_cvt_pk_bf16_f32 v38, v44, v45
	v_cvt_pk_bf16_f32 v39, v34, v35
	v_cvt_pk_bf16_f32 v40, v40, v41
	v_cvt_pk_bf16_f32 v41, v36, v37
	v_mov_b32_e32 v232, v38
	v_mov_b32_e32 v233, v39
	v_mov_b32_e32 v234, v40
	v_mov_b32_e32 v235, v41
	v_pk_mul_f32 v[22:23], v[22:23], v[148:149] op_sel_hi:[1,0]
	v_pk_mul_f32 v[36:37], v[20:21], v[148:149] op_sel_hi:[1,0]
	v_pk_mul_f32 v[34:35], v[18:19], v[148:149] op_sel_hi:[1,0]
	v_pk_mul_f32 v[38:39], v[16:17], v[148:149] op_sel_hi:[1,0]
	v_pk_mul_f32 v[18:19], v[30:31], v[148:149] op_sel_hi:[1,0]
	v_pk_mul_f32 v[28:29], v[28:29], v[148:149] op_sel_hi:[1,0]
	v_pk_mul_f32 v[20:21], v[26:27], v[148:149] op_sel_hi:[1,0]
	s_and_b64 vcc, exec, s[38:39]
	v_pk_mul_f32 v[24:25], v[24:25], v[148:149] op_sel_hi:[1,0]
	s_cbranch_vccnz .LBB0_575
	v_mul_f32_e32 v16, v37, v37
	v_mul_f32_e32 v17, v23, v23
	v_fmac_f32_e32 v16, v36, v36
	v_fmac_f32_e32 v17, v22, v22
	v_add_f32_e32 v16, v16, v17
	v_mul_f32_e32 v17, v39, v39
	v_mul_f32_e32 v26, v35, v35
	v_fmac_f32_e32 v17, v38, v38
	v_fmac_f32_e32 v26, v34, v34
	v_add_f32_e32 v17, v17, v26
	v_add_f32_e32 v16, v16, v17
	v_mul_f32_e32 v17, v29, v29
	v_mul_f32_e32 v26, v19, v19
	v_fmac_f32_e32 v17, v28, v28
	v_fmac_f32_e32 v26, v18, v18
	v_add_f32_e32 v17, v17, v26
	v_add_f32_e32 v16, v17, v16
	v_mul_f32_e32 v17, v25, v25
	v_mul_f32_e32 v26, v21, v21
	v_fmac_f32_e32 v17, v24, v24
	v_fmac_f32_e32 v26, v20, v20
	v_add_f32_e32 v17, v17, v26
	v_add_f32_e32 v16, v17, v16
	v_mov_b32_e32 v17, v16
	s_nop 1
	v_permlane16_swap_b32_e32 v16, v17
	v_add_f32_e32 v16, v16, v17
	v_mov_b32_e32 v17, v16
	s_nop 1
	v_permlane32_swap_b32_e32 v16, v17
	v_add_f32_e32 v16, v16, v17
	v_fmamk_f32 v16, v16, 0x3c800000, v201
	v_rsq_f32_e32 v16, v16
	s_waitcnt lgkmcnt(0)
	v_pk_mul_f32 v[26:27], v[124:125], v[36:37]
	v_pk_mul_f32 v[22:23], v[126:127], v[22:23]
	v_pk_mul_f32 v[30:31], v[120:121], v[38:39]
	v_pk_mul_f32 v[36:37], v[26:27], v[16:17] op_sel_hi:[1,0]
	v_pk_mul_f32 v[26:27], v[122:123], v[34:35]
	v_pk_mul_f32 v[18:19], v[118:119], v[18:19]
	v_pk_mul_f32 v[34:35], v[26:27], v[16:17] op_sel_hi:[1,0]
	v_pk_mul_f32 v[26:27], v[116:117], v[28:29]
	v_pk_mul_f32 v[20:21], v[114:115], v[20:21]
	v_pk_mul_f32 v[24:25], v[112:113], v[24:25]
	v_pk_mul_f32 v[22:23], v[22:23], v[16:17] op_sel_hi:[1,0]
	v_pk_mul_f32 v[38:39], v[30:31], v[16:17] op_sel_hi:[1,0]
	v_pk_mul_f32 v[18:19], v[18:19], v[16:17] op_sel_hi:[1,0]
	v_pk_mul_f32 v[28:29], v[26:27], v[16:17] op_sel_hi:[1,0]
	v_pk_mul_f32 v[20:21], v[20:21], v[16:17] op_sel_hi:[1,0]
	v_pk_mul_f32 v[24:25], v[24:25], v[16:17] op_sel_hi:[1,0]

; __device__ __forceinline__ void st16_wt(void* p, u32x4 v) { if (WT_STORES) asm volatile("global_store_dwordx4 %0, %1, off sc1\n\ts_nop 1" :: "v"(p), "v"(v) : "memory"); else *(u32x4*)p = v; }
; __device__ __forceinline__ unsigned cvt_pk_bf16(float lo, float hi) { unsigned r; asm volatile("v_cvt_pk_bf16_f32 %0, %1, %2" : "=v"(r) : "v"(lo), "v"(hi)); return r; }
; #define PG8_ZERO4(x) do { unsigned long long z0_, z1_; asm volatile("v_mov_b64 %0, 0\n\tv_mov_b64 %1, 0" : "=v"(z0_), "=v"(z1_)); typedef unsigned long long u64x2_ __attribute__((ext_vector_type(2))); (x) = __builtin_bit_cast(f32x4, (u64x2_){z0_, z1_}); } while (0)
;     __device__ __forceinline__ void operator()(const f32x4 (&acc)[2][2][4][2], const Unit& u, int wr, int wc, int fr, int fq, const bool reuse, PG8_LAS float* rscr, PG8_LAS const float* gains) const {
;     ...
;                 bf16_t* p = p0 + (size_t)(8 * ai + m) * step16;
; #pragma unroll
;                 for (int bj = 0; bj < 2; ++bj) { u32x4 w; w.x = cvt_pk_bf16(v[bj][0][0], v[bj][0][1]); w.y = cvt_pk_bf16(v[bj][0][2], v[bj][0][3]); w.z = cvt_pk_bf16(v[bj][1][0], v[bj][1][1]); w.w = cvt_pk_bf16(v[bj][1][2], v[bj][1][3]);
;                     st16_wt(p + 32 * bj, w); }
;     ...
; #pragma unroll
;         for (int a = 0; a < 2; ++a)
; #pragma unroll
;             for (int b = 0; b < 2; ++b)
; #pragma unroll
;                 for (int m = 0; m < 4; ++m)
; #pragma unroll
;                     for (int n = 0; n < 2; ++n) PG8_ZERO4(acc[a][b][m][n]);
;         cur = nxt; cA = nA; cB = nB; ++ui;
.LBB0_577:
	v_lshl_add_u64 v[10:11], v[16:17], 0, s[12:13]
	v_cvt_pk_bf16_f32 v14, v18, v19
	v_cvt_pk_bf16_f32 v15, v6, v7
	v_cvt_pk_bf16_f32 v16, v20, v21
	v_cvt_pk_bf16_f32 v17, v4, v5
	v_mov_b32_e32 v244, v14
	v_mov_b32_e32 v245, v15
	v_mov_b32_e32 v246, v16
	v_mov_b32_e32 v247, v17
	v_cvt_pk_bf16_f32 v4, v12, v13
	v_cvt_pk_bf16_f32 v5, v0, v1
	v_cvt_pk_bf16_f32 v6, v8, v9
	v_cvt_pk_bf16_f32 v7, v2, v3
	s_andn2_b64 vcc, exec, s[36:37]
	s_mov_b64 s[22:23], -1
	v_mov_b32_e32 v248, v4
	v_mov_b32_e32 v249, v5
	v_mov_b32_e32 v250, v6
	v_mov_b32_e32 v251, v7
	s_mov_b32 s101, 7
	s_cbranch_vccnz .LBB0_524
	s_andn2_b64 vcc, exec, s[8:9]
	v_mov_b64 v[132:133], 0
	v_mov_b64 v[134:135], 0
	v_mov_b64 v[128:129], 0
	v_mov_b64 v[130:131], 0
	v_mov_b64 v[100:101], 0
	v_mov_b64 v[102:103], 0
	v_mov_b64 v[96:97], 0
	v_mov_b64 v[98:99], 0
	v_mov_b64 v[84:85], 0
	v_mov_b64 v[86:87], 0
	v_mov_b64 v[80:81], 0
	v_mov_b64 v[82:83], 0
	v_mov_b64 v[68:69], 0
	v_mov_b64 v[70:71], 0
	v_mov_b64 v[64:65], 0
	v_mov_b64 v[66:67], 0
	v_mov_b64 v[140:141], 0
	v_mov_b64 v[142:143], 0
	v_mov_b64 v[136:137], 0
	v_mov_b64 v[138:139], 0
	v_mov_b64 v[108:109], 0
	v_mov_b64 v[110:111], 0
	v_mov_b64 v[104:105], 0
	v_mov_b64 v[106:107], 0
	v_mov_b64 v[92:93], 0
	v_mov_b64 v[94:95], 0
	v_mov_b64 v[88:89], 0
	v_mov_b64 v[90:91], 0
	v_mov_b64 v[76:77], 0
	v_mov_b64 v[78:79], 0
	v_mov_b64 v[72:73], 0
	v_mov_b64 v[74:75], 0
	v_mov_b64 v[52:53], 0
	v_mov_b64 v[54:55], 0
	v_mov_b64 v[48:49], 0
	v_mov_b64 v[50:51], 0
	v_mov_b64 v[36:37], 0
	v_mov_b64 v[38:39], 0
	v_mov_b64 v[32:33], 0
	v_mov_b64 v[34:35], 0
	v_mov_b64 v[20:21], 0
	v_mov_b64 v[22:23], 0
	v_mov_b64 v[16:17], 0
	v_mov_b64 v[18:19], 0
	v_mov_b64 v[4:5], 0
	v_mov_b64 v[6:7], 0
	v_mov_b64 v[0:1], 0
	v_mov_b64 v[2:3], 0
	v_mov_b64 v[60:61], 0
	v_mov_b64 v[62:63], 0
	v_mov_b64 v[56:57], 0
	v_mov_b64 v[58:59], 0
	v_mov_b64 v[44:45], 0
	v_mov_b64 v[46:47], 0
	v_mov_b64 v[40:41], 0
	v_mov_b64 v[42:43], 0
	v_mov_b64 v[28:29], 0
	v_mov_b64 v[30:31], 0
	v_mov_b64 v[24:25], 0
	v_mov_b64 v[26:27], 0
	v_mov_b64 v[12:13], 0
	v_mov_b64 v[14:15], 0
	v_mov_b64 v[8:9], 0
	v_mov_b64 v[10:11], 0
	s_cbranch_vccnz .LBB0_523
	s_barrier
	s_branch .LBB0_523
.LBB0_580:
	s_cmp_eq_u32 s101, 0
	s_cbranch_scc1 .Lpkb_fd
	global_store_dwordx4 v[254:255], v[206:209], off offset:64
	v_add_co_u32_e32 v254, vcc, s100, v254
	s_nop 1
	v_addc_co_u32_e32 v255, vcc, 0, v255, vcc
	global_store_dwordx4 v[254:255], v[228:231], off
	global_store_dwordx4 v[254:255], v[232:235], off offset:64
	v_add_co_u32_e32 v254, vcc, s100, v254
	s_nop 1
	v_addc_co_u32_e32 v255, vcc, 0, v255, vcc
	global_store_dwordx4 v[254:255], v[236:239], off
	global_store_dwordx4 v[254:255], v[240:243], off offset:64
	v_add_co_u32_e32 v254, vcc, s100, v254
	s_nop 1
	v_addc_co_u32_e32 v255, vcc, 0, v255, vcc
	global_store_dwordx4 v[254:255], v[244:247], off
	global_store_dwordx4 v[254:255], v[248:251], off offset:64
	s_mov_b32 s101, 0
